# gdn_prep rhs stage (sv*=beta, sk*=beta*exp(gc)): batched ds_read2/ds_write2 instead of 16 dependent round trips; selected-branch K-fragment wait made lgkmcnt-overflow safe
# baseline (speedup 1.0000x reference)
; DI void phase_gdn_prep(const Params& p, int l, char* smem) {
;     ...
;         {
;             const int t = tid >> 2, part = tid & 3;
;             const float bt = sbeta[t], be = bt * __expf(sgc[t]);
; #pragma unroll
;             for (int j = 0; j < 16; ++j) { sv[t * 65 + part * 16 + j] *= bt; sk[t * 65 + part * 16 + j] *= be; }
;         }
;         __syncthreads();
;         { const int nxt = item + (int)gridDim.x; prefetch(nxt < 3072 ? nxt : item); }
.LBB0_313:
	s_or_b64 exec, exec, s[4:5]
	v_mul_f32_e32 v0, v0, v185
	v_mul_f32_e32 v1, v1, v185
	v_mul_f32_e32 v2, v2, v185
	v_mul_f32_e32 v3, v3, v185
	v_mul_f32_e32 v0, v0, v12
	v_mul_f32_e32 v1, v1, v4
	v_mul_f32_e32 v2, v2, v5
	v_mul_f32_e32 v3, v3, v6
	v_cndmask_b32_e64 v0, 0, v0, s[16:17]
	v_cndmask_b32_e64 v1, 0, v1, s[20:21]
	v_cndmask_b32_e64 v2, 0, v2, s[24:25]
	v_mul_f32_e32 v5, v30, v5
	v_mul_f32_e32 v7, v28, v12
	v_mul_f32_e32 v4, v29, v4
	v_cndmask_b32_e64 v3, 0, v3, s[28:29]
	v_mul_f32_e32 v6, v31, v6
	ds_write_b128 v145, v[0:3] offset:50112
	v_cvt_pk_bf16_f32 v0, v7, v4
	v_cvt_pk_bf16_f32 v1, v5, v6
	global_store_dwordx2 v[20:21], v[0:1], off offset:72
	v_add_u32_e32 v1, 0x8200, v118
	ds_read_b32 v2, v74
	ds_read_b32 v0, v71
	ds_read2_b32 v[4:5], v1 offset0:0 offset1:1
	ds_read2_b32 v[6:7], v1 offset0:2 offset1:3
	ds_read2_b32 v[8:9], v1 offset0:4 offset1:5
	ds_read2_b32 v[10:11], v1 offset0:6 offset1:7
	ds_read2_b32 v[12:13], v1 offset0:8 offset1:9
	ds_read2_b32 v[14:15], v1 offset0:10 offset1:11
	ds_read2_b32 v[16:17], v1 offset0:12 offset1:13
	ds_read2_b32 v[18:19], v1 offset0:14 offset1:15
	v_readlane_b32 s4, v249, 16
	s_add_i32 s30, s86, s4
	s_cmpk_gt_i32 s30, 0xbff
	v_readlane_b32 s5, v249, 17
	s_cselect_b64 s[90:91], -1, 0
	s_cmpk_lt_i32 s30, 0xc00
	s_cselect_b32 s5, s30, s86
	s_ashr_i32 s6, s5, 8
	s_mul_hi_i32 s4, s6, 0x2aaaaaab
	s_lshr_b32 s7, s4, 31
	s_add_i32 s4, s4, s7
	s_mul_i32 s7, s4, 6
	s_lshl_b32 s5, s5, 6
	s_sub_i32 s86, s6, s7
	s_and_b32 s6, s5, 0x3fc0
	s_ashr_i32 s5, s4, 31
	s_sub_i32 s8, 2, s6
	s_lshl_b64 s[92:93], s[4:5], 14
	s_lshl_b32 s94, s86, 6
	v_cmp_lt_i32_e32 vcc, s8, v46
	s_or_b32 s92, s92, s6
	s_ashr_i32 s95, s94, 31
	s_and_b64 s[96:97], s[42:43], vcc
	s_waitcnt lgkmcnt(0)
	ds_read2_b32 v[20:21], v59 offset0:0 offset1:1
	ds_read2_b32 v[22:23], v59 offset0:2 offset1:3
	ds_read2_b32 v[24:25], v59 offset0:4 offset1:5
	ds_read2_b32 v[26:27], v59 offset0:6 offset1:7
	ds_read2_b32 v[28:29], v59 offset0:8 offset1:9
	ds_read2_b32 v[30:31], v59 offset0:10 offset1:11
	ds_read2_b32 v[32:33], v59 offset0:12 offset1:13
	ds_read2_b32 v[34:35], v59 offset0:14 offset1:15
	v_mul_f32_e32 v0, 0x3fb8aa3b, v0
	v_exp_f32_e32 v0, v0
	v_pk_mul_f32 v[4:5], v[2:3], v[4:5] op_sel_hi:[0,1]
	v_pk_mul_f32 v[6:7], v[2:3], v[6:7] op_sel_hi:[0,1]
	v_pk_mul_f32 v[8:9], v[2:3], v[8:9] op_sel_hi:[0,1]
	v_pk_mul_f32 v[10:11], v[2:3], v[10:11] op_sel_hi:[0,1]
	v_pk_mul_f32 v[12:13], v[2:3], v[12:13] op_sel_hi:[0,1]
	v_pk_mul_f32 v[14:15], v[2:3], v[14:15] op_sel_hi:[0,1]
	v_pk_mul_f32 v[16:17], v[2:3], v[16:17] op_sel_hi:[0,1]
	v_pk_mul_f32 v[18:19], v[2:3], v[18:19] op_sel_hi:[0,1]
	v_mul_f32_e32 v0, v2, v0
	s_waitcnt lgkmcnt(0)
	ds_write2_b32 v1, v4, v5 offset0:0 offset1:1
	ds_write2_b32 v1, v6, v7 offset0:2 offset1:3
	ds_write2_b32 v1, v8, v9 offset0:4 offset1:5
	ds_write2_b32 v1, v10, v11 offset0:6 offset1:7
	ds_write2_b32 v1, v12, v13 offset0:8 offset1:9
	ds_write2_b32 v1, v14, v15 offset0:10 offset1:11
	ds_write2_b32 v1, v16, v17 offset0:12 offset1:13
	ds_write2_b32 v1, v18, v19 offset0:14 offset1:15
	v_pk_mul_f32 v[20:21], v[0:1], v[20:21] op_sel_hi:[0,1]
	v_pk_mul_f32 v[22:23], v[0:1], v[22:23] op_sel_hi:[0,1]
	v_pk_mul_f32 v[24:25], v[0:1], v[24:25] op_sel_hi:[0,1]
	v_pk_mul_f32 v[26:27], v[0:1], v[26:27] op_sel_hi:[0,1]
	v_pk_mul_f32 v[28:29], v[0:1], v[28:29] op_sel_hi:[0,1]
	v_pk_mul_f32 v[30:31], v[0:1], v[30:31] op_sel_hi:[0,1]
	v_pk_mul_f32 v[32:33], v[0:1], v[32:33] op_sel_hi:[0,1]
	v_pk_mul_f32 v[34:35], v[0:1], v[34:35] op_sel_hi:[0,1]
	ds_write2_b32 v59, v20, v21 offset0:0 offset1:1
	ds_write2_b32 v59, v22, v23 offset0:2 offset1:3
	ds_write2_b32 v59, v24, v25 offset0:4 offset1:5
	ds_write2_b32 v59, v26, v27 offset0:6 offset1:7
	ds_write2_b32 v59, v28, v29 offset0:8 offset1:9
	ds_write2_b32 v59, v30, v31 offset0:10 offset1:11
	ds_write2_b32 v59, v32, v33 offset0:12 offset1:13
	ds_write2_b32 v59, v34, v35 offset0:14 offset1:15
	v_mov_b32_e32 v24, 0
	v_mov_b32_e32 v25, 0
	v_mov_b32_e32 v26, 0
	v_mov_b32_e32 v27, 0
	s_waitcnt lgkmcnt(0)
	s_barrier
	s_and_saveexec_b64 s[4:5], s[96:97]
	s_cbranch_execz .LBB0_315
	v_readlane_b32 s52, v250, 51
	v_readlane_b32 s56, v250, 55
	v_readlane_b32 s57, v250, 56
	v_lshl_add_u64 v[0:1], s[92:93], 0, v[46:47]
	s_movk_i32 s2, 0x1800
	v_mov_b64_e32 v[2:3], s[56:57]
	v_mad_u64_u32 v[2:3], s[6:7], v0, s2, v[2:3]
	v_mov_b32_e32 v0, v3
	v_mad_u64_u32 v[0:1], s[6:7], v1, s2, v[0:1]
	v_mov_b32_e32 v3, v0
	v_lshl_add_u64 v[0:1], s[94:95], 1, v[2:3]
	v_lshlrev_b32_e32 v188, 1, v48
	v_lshl_add_u64 v[0:1], v[0:1], 0, v[188:189]
	v_add_co_u32_e32 v0, vcc, 0xffffc000, v0
	v_readlane_b32 s53, v250, 52
	s_nop 0
	v_addc_co_u32_e32 v1, vcc, -1, v1, vcc
	global_load_dwordx4 v[24:27], v[0:1], off offset:-2048
	v_readlane_b32 s54, v250, 53
	v_readlane_b32 s55, v250, 54
	v_readlane_b32 s58, v250, 57
	v_readlane_b32 s59, v250, 58
	v_readlane_b32 s60, v250, 59
	v_readlane_b32 s61, v250, 60
	v_readlane_b32 s62, v250, 61
	v_readlane_b32 s63, v250, 62
	v_readlane_b32 s64, v250, 63
	v_readlane_b32 s65, v249, 0
	v_readlane_b32 s66, v249, 1
	v_readlane_b32 s67, v249, 2

; DI void nsa_item(const Params& p, int bk, int qb, char* smem, float Mb) {
;     ...
; #pragma unroll
;                 for (int g = 0; g < 3; ++g) {
;                     f32x4 st[4];
;                     st_from(kf, qf[g], st, -Ml);
;                     if (diag) {
; #pragma unroll
;                         for (int k4 = 0; k4 < 4; ++k4)
; #pragma unroll
;                             for (int ii = 0; ii < 4; ++ii) {
;                                 const float pv = (j * 64 + k4 * 16 + fq * 4 + ii <= tq) ? __builtin_amdgcn_exp2f(st[k4][ii]) : 0.f;
;                                 st[k4][ii] = pv; ls[g] += pv;
;                             }
;                     } else {
; #pragma unroll
;                         for (int k4 = 0; k4 < 4; ++k4)
; #pragma unroll
;                             for (int ii = 0; ii < 4; ++ii) { const float pv = __builtin_amdgcn_exp2f(st[k4][ii]); st[k4][ii] = pv; ls[g] += pv; }
;                     }
;                     pv_from(vf, st, o[g]);
;                 }
.Lsel_fast:
	ds_read_b128 v[140:143], v116 offset:6976
	ds_read_b128 v[108:111], v116 offset:9216
	ds_read_b128 v[88:91], v116 offset:9280
	ds_read_b128 v[92:95], v116 offset:11520
	ds_read_b128 v[96:99], v116 offset:11584
	ds_read_b128 v[100:103], v116 offset:13824
	ds_read_b128 v[104:107], v116 offset:13888
	ds_read_b128 v[112:115], v116 offset:16128
	s_waitcnt lgkmcnt(7)
	ds_read_b128 v[116:119], v116 offset:16192
	v_mfma_f32_16x16x32_bf16 v[156:159], v[120:123], v[0:3], v[124:127]
	v_mfma_f32_16x16x32_bf16 v[164:167], v[132:135], v[0:3], v[124:127]
	v_mfma_f32_16x16x32_bf16 v[172:175], v[144:147], v[0:3], v[124:127]
	v_mfma_f32_16x16x32_bf16 v[180:183], v[152:155], v[0:3], v[124:127]
	v_mfma_f32_16x16x32_bf16 v[156:159], v[128:131], v[4:7], v[156:159]
	v_mfma_f32_16x16x32_bf16 v[164:167], v[136:139], v[4:7], v[164:167]
	v_mfma_f32_16x16x32_bf16 v[172:175], v[148:151], v[4:7], v[172:175]
	v_mfma_f32_16x16x32_bf16 v[180:183], v[140:143], v[4:7], v[180:183]
	v_mfma_f32_16x16x32_bf16 v[184:187], v[120:123], v[8:11], v[124:127]
	v_mfma_f32_16x16x32_bf16 v[176:179], v[132:135], v[8:11], v[124:127]
	v_mfma_f32_16x16x32_bf16 v[168:171], v[144:147], v[8:11], v[124:127]
	v_mfma_f32_16x16x32_bf16 v[160:163], v[152:155], v[8:11], v[124:127]
	s_nop 1
	v_mfma_f32_16x16x32_bf16 v[184:187], v[128:131], v[12:15], v[184:187]
	v_exp_f32_e32 v156, v156
	v_exp_f32_e32 v157, v157
	v_exp_f32_e32 v158, v158
	v_exp_f32_e32 v159, v159
	v_mfma_f32_16x16x32_bf16 v[176:179], v[136:139], v[12:15], v[176:179]
	v_exp_f32_e32 v164, v164
	v_exp_f32_e32 v165, v165
	v_exp_f32_e32 v166, v166
	v_exp_f32_e32 v167, v167
	v_mfma_f32_16x16x32_bf16 v[168:171], v[148:151], v[12:15], v[168:171]
	v_exp_f32_e32 v172, v172
	v_exp_f32_e32 v173, v173
	v_exp_f32_e32 v174, v174
	v_exp_f32_e32 v175, v175
	v_mfma_f32_16x16x32_bf16 v[160:163], v[140:143], v[12:15], v[160:163]
	v_exp_f32_e32 v180, v180
	v_exp_f32_e32 v181, v181
	v_exp_f32_e32 v182, v182
	v_exp_f32_e32 v183, v183
	v_pk_add_f32 v[254:255], v[156:157], v[158:159]
	v_pk_add_f32 v[254:255], v[254:255], v[164:165]
	v_pk_add_f32 v[254:255], v[254:255], v[166:167]
	v_cvt_pk_bf16_f32 v156, v156, v157
	v_cvt_pk_bf16_f32 v157, v158, v159
	v_cvt_pk_bf16_f32 v158, v164, v165
	v_cvt_pk_bf16_f32 v159, v166, v167
	v_pk_add_f32 v[164:165], v[172:173], v[174:175]
	v_pk_add_f32 v[164:165], v[164:165], v[180:181]
	v_pk_add_f32 v[164:165], v[164:165], v[182:183]
	v_cvt_pk_bf16_f32 v172, v172, v173
	v_cvt_pk_bf16_f32 v173, v174, v175
	v_cvt_pk_bf16_f32 v174, v180, v181
	v_cvt_pk_bf16_f32 v175, v182, v183
	v_pk_add_f32 v[254:255], v[254:255], v[164:165]
	v_add_f32_e32 v244, v244, v254
	v_add_f32_e32 v244, v244, v255
	s_waitcnt lgkmcnt(0)
; DI void nsa_item(const Params& p, int bk, int qb, char* smem, float Mb) {
;     ...
; #pragma unroll
;                 for (int g = 0; g < 3; ++g) {
;                     f32x4 st[4];
;                     st_from(kf, qf[g], st, -Ml);
;                     if (diag) {
; #pragma unroll
;                         for (int k4 = 0; k4 < 4; ++k4)
; #pragma unroll
;                             for (int ii = 0; ii < 4; ++ii) {
;                                 const float pv = (j * 64 + k4 * 16 + fq * 4 + ii <= tq) ? __builtin_amdgcn_exp2f(st[k4][ii]) : 0.f;
;                                 st[k4][ii] = pv; ls[g] += pv;
;                             }
;                     } else {
; #pragma unroll
;                         for (int k4 = 0; k4 < 4; ++k4)
; #pragma unroll
;                             for (int ii = 0; ii < 4; ++ii) { const float pv = __builtin_amdgcn_exp2f(st[k4][ii]); st[k4][ii] = pv; ls[g] += pv; }
;                     }
;                     pv_from(vf, st, o[g]);
;                 }
	s_nop 1
	v_mfma_f32_16x16x32_bf16 v[68:71], v[108:111], v[156:159], v[68:71]
	v_exp_f32_e32 v184, v184
	v_mfma_f32_16x16x32_bf16 v[64:67], v[92:95], v[156:159], v[64:67]
	v_exp_f32_e32 v185, v185
	v_mfma_f32_16x16x32_bf16 v[60:63], v[100:103], v[156:159], v[60:63]
	v_exp_f32_e32 v186, v186
	v_mfma_f32_16x16x32_bf16 v[56:59], v[112:115], v[156:159], v[56:59]
	v_exp_f32_e32 v187, v187
	v_mfma_f32_16x16x32_bf16 v[68:71], v[88:91], v[172:175], v[68:71]
	v_exp_f32_e32 v176, v176
	v_mfma_f32_16x16x32_bf16 v[64:67], v[96:99], v[172:175], v[64:67]
	v_exp_f32_e32 v177, v177
	v_mfma_f32_16x16x32_bf16 v[60:63], v[104:107], v[172:175], v[60:63]
	v_exp_f32_e32 v178, v178
	v_mfma_f32_16x16x32_bf16 v[56:59], v[116:119], v[172:175], v[56:59]
	v_exp_f32_e32 v179, v179
	v_mfma_f32_16x16x32_bf16 v[156:159], v[120:123], v[16:19], v[124:127]
	v_exp_f32_e32 v168, v168
	v_mfma_f32_16x16x32_bf16 v[164:167], v[132:135], v[16:19], v[124:127]
	v_exp_f32_e32 v169, v169
	v_mfma_f32_16x16x32_bf16 v[172:175], v[144:147], v[16:19], v[124:127]
	v_exp_f32_e32 v170, v170
	v_mfma_f32_16x16x32_bf16 v[180:183], v[152:155], v[16:19], v[124:127]
	v_exp_f32_e32 v171, v171
	v_mfma_f32_16x16x32_bf16 v[156:159], v[128:131], v[20:23], v[156:159]
	v_exp_f32_e32 v160, v160
	v_mfma_f32_16x16x32_bf16 v[164:167], v[136:139], v[20:23], v[164:167]
	v_exp_f32_e32 v161, v161
	v_mfma_f32_16x16x32_bf16 v[172:175], v[148:151], v[20:23], v[172:175]
	v_exp_f32_e32 v162, v162
	v_mfma_f32_16x16x32_bf16 v[180:183], v[140:143], v[20:23], v[180:183]
	v_exp_f32_e32 v163, v163
	v_pk_add_f32 v[254:255], v[184:185], v[186:187]
	v_pk_add_f32 v[254:255], v[254:255], v[176:177]
	v_pk_add_f32 v[254:255], v[254:255], v[178:179]
	v_cvt_pk_bf16_f32 v184, v184, v185
	v_cvt_pk_bf16_f32 v185, v186, v187
	v_cvt_pk_bf16_f32 v186, v176, v177
	v_cvt_pk_bf16_f32 v187, v178, v179
	v_pk_add_f32 v[176:177], v[168:169], v[170:171]
	v_pk_add_f32 v[176:177], v[176:177], v[160:161]
	v_pk_add_f32 v[176:177], v[176:177], v[162:163]
	v_cvt_pk_bf16_f32 v168, v168, v169
	v_cvt_pk_bf16_f32 v169, v170, v171
	v_cvt_pk_bf16_f32 v170, v160, v161
	v_cvt_pk_bf16_f32 v171, v162, v163
	v_pk_add_f32 v[254:255], v[254:255], v[176:177]
	v_add_f32_e32 v243, v243, v254
	v_add_f32_e32 v243, v243, v255
	s_nop 1
	v_mfma_f32_16x16x32_bf16 v[52:55], v[108:111], v[184:187], v[52:55]
	v_exp_f32_e32 v156, v156
	v_exp_f32_e32 v157, v157
	v_mfma_f32_16x16x32_bf16 v[48:51], v[92:95], v[184:187], v[48:51]
	v_exp_f32_e32 v158, v158
	v_exp_f32_e32 v159, v159
	v_mfma_f32_16x16x32_bf16 v[44:47], v[100:103], v[184:187], v[44:47]
	v_exp_f32_e32 v164, v164
	v_exp_f32_e32 v165, v165
	v_mfma_f32_16x16x32_bf16 v[40:43], v[112:115], v[184:187], v[40:43]
	v_exp_f32_e32 v166, v166
	v_exp_f32_e32 v167, v167
	v_mfma_f32_16x16x32_bf16 v[52:55], v[88:91], v[168:171], v[52:55]
	v_exp_f32_e32 v172, v172
	v_exp_f32_e32 v173, v173
	v_mfma_f32_16x16x32_bf16 v[48:51], v[96:99], v[168:171], v[48:51]
	v_exp_f32_e32 v174, v174
	v_exp_f32_e32 v175, v175
	v_mfma_f32_16x16x32_bf16 v[44:47], v[104:107], v[168:171], v[44:47]
	v_exp_f32_e32 v180, v180
	v_exp_f32_e32 v181, v181
	v_mfma_f32_16x16x32_bf16 v[40:43], v[116:119], v[168:171], v[40:43]
	v_exp_f32_e32 v182, v182
	v_exp_f32_e32 v183, v183
	v_pk_add_f32 v[254:255], v[156:157], v[158:159]
	v_pk_add_f32 v[254:255], v[254:255], v[164:165]
	v_pk_add_f32 v[254:255], v[254:255], v[166:167]
	v_cvt_pk_bf16_f32 v156, v156, v157
	v_cvt_pk_bf16_f32 v157, v158, v159
	v_cvt_pk_bf16_f32 v158, v164, v165
	v_cvt_pk_bf16_f32 v159, v166, v167
	v_pk_add_f32 v[164:165], v[172:173], v[174:175]
	v_pk_add_f32 v[164:165], v[164:165], v[180:181]
	v_pk_add_f32 v[164:165], v[164:165], v[182:183]
	v_cvt_pk_bf16_f32 v172, v172, v173
	v_cvt_pk_bf16_f32 v173, v174, v175
	v_cvt_pk_bf16_f32 v174, v180, v181
	v_cvt_pk_bf16_f32 v175, v182, v183
	v_pk_add_f32 v[254:255], v[254:255], v[164:165]
	v_add_f32_e32 v241, v241, v254
	v_add_f32_e32 v241, v241, v255
	s_nop 1
	v_mfma_f32_16x16x32_bf16 v[36:39], v[108:111], v[156:159], v[36:39]
	v_mfma_f32_16x16x32_bf16 v[32:35], v[92:95], v[156:159], v[32:35]
	v_mfma_f32_16x16x32_bf16 v[28:31], v[100:103], v[156:159], v[28:31]
	v_mfma_f32_16x16x32_bf16 v[24:27], v[112:115], v[156:159], v[24:27]
	v_mfma_f32_16x16x32_bf16 v[36:39], v[88:91], v[172:175], v[36:39]
	v_mfma_f32_16x16x32_bf16 v[32:35], v[96:99], v[172:175], v[32:35]
	v_mfma_f32_16x16x32_bf16 v[28:31], v[104:107], v[172:175], v[28:31]
	v_mfma_f32_16x16x32_bf16 v[24:27], v[116:119], v[172:175], v[24:27]
	s_branch .LBB0_534
